# ffn_in: the last partial round of 128 tiles is spread over all 8 XCDs (16 per XCD) instead of 4 XCDs
# baseline (speedup 1.0000x reference)
.LBB0_1657:
	s_andn2_b64 vcc, exec, s[26:27]
	s_cbranch_vccnz .LBB0_1659
	s_lshl_b32 s1, s64, 3
	v_readlane_b32 s25, v244, 22
	s_or_b32 s1, s1, s25
	v_readlane_b32 s25, v244, 23
	s_mul_i32 s1, s1, s25
	v_readlane_b32 s25, v244, 24
	s_add_i32 s1, s1, s25
	s_cmp_eq_u32 s64, 5
	s_cbranch_scc0 .Lfi_keep
	v_readlane_b32 s1, v244, 22
	s_nop 3
	s_lshl_b32 s1, s1, 4
	s_add_i32 s1, s1, s25
	s_add_i32 s1, s1, 0x500
	s_cmp_lt_u32 s25, 16
	s_cselect_b32 s1, s1, 0x580
.Lfi_keep:
.LBB0_1659:
	s_cmpk_lt_i32 s1, 0x580
	s_cselect_b64 s[40:41], -1, 0
	s_cmpk_gt_i32 s1, 0x57f
	s_cselect_b64 s[26:27], -1, 0
	s_mov_b32 s28, 0
	s_and_b64 vcc, exec, s[26:27]
	s_mov_b32 s30, 0
	s_cbranch_vccnz .LBB0_1664
	s_mov_b64 s[44:45], -1
	s_and_b64 vcc, exec, s[36:37]
	s_mul_hi_i32 s25, s1, 0x2e8ba2e9
	s_cbranch_vccnz .LBB0_1662
	s_lshr_b32 s28, s25, 31
	s_ashr_i32 s29, s25, 2
	s_add_i32 s28, s29, s28
	s_mul_i32 s29, s28, 22
	s_sub_i32 s30, s1, s29
	s_mov_b64 s[44:45], 0
